# attention first halves: second score tile's K fragments prefetched two MFMAs ahead using spare registers
# baseline (speedup 1.0000x reference)
.LBB0_813:
	v_exp_f32_e32 v50, v50
	v_exp_f32_e32 v51, v51
	s_waitcnt lgkmcnt(0)
	v_mfma_f32_32x32x16_bf16 v[82:97], v[98:101], v[114:117], v[34:49]
	v_exp_f32_e32 v52, v52
	v_exp_f32_e32 v53, v53
	v_exp_f32_e32 v54, v54
	v_exp_f32_e32 v55, v55
	v_exp_f32_e32 v56, v56
	v_exp_f32_e32 v57, v57
	v_mfma_f32_32x32x16_bf16 v[82:97], v[102:105], v[118:121], v[82:97]
	ds_read_b128 v[98:101], v201 offset:13376
	ds_read_b128 v[102:105], v201 offset:13408
	v_exp_f32_e32 v58, v58
	v_exp_f32_e32 v59, v59
	v_exp_f32_e32 v60, v60
	v_exp_f32_e32 v61, v61
	v_exp_f32_e32 v62, v62
	v_exp_f32_e32 v63, v63
	s_waitcnt lgkmcnt(0)
	v_mfma_f32_32x32x16_bf16 v[82:97], v[98:101], v[122:125], v[82:97]
	v_exp_f32_e32 v64, v64
	v_exp_f32_e32 v65, v65
	v_exp_f32_e32 v66, v66
	v_exp_f32_e32 v67, v67
	v_exp_f32_e32 v68, v68
	v_exp_f32_e32 v69, v69
	v_exp_f32_e32 v70, v70
	v_mfma_f32_32x32x16_bf16 v[82:97], v[102:105], v[126:129], v[82:97]
	ds_read_b128 v[98:101], v201 offset:13440
	ds_read_b128 v[102:105], v201 offset:13472
	ds_read_b128 v[170:173], v201 offset:19968
	ds_read_b128 v[174:177], v201 offset:20000
	ds_read_b128 v[242:245], v201 offset:20032
	ds_read_b128 v[246:249], v201 offset:20064
	v_exp_f32_e32 v71, v71
	v_exp_f32_e32 v72, v72
	v_exp_f32_e32 v73, v73
	v_exp_f32_e32 v74, v74
	v_exp_f32_e32 v75, v75
	s_waitcnt lgkmcnt(4)
	v_mfma_f32_32x32x16_bf16 v[82:97], v[98:101], v[130:133], v[82:97]
	v_exp_f32_e32 v76, v76
	v_exp_f32_e32 v77, v77
	v_exp_f32_e32 v78, v78
	v_exp_f32_e32 v79, v79
	v_exp_f32_e32 v80, v80
	v_exp_f32_e32 v81, v81
	v_mfma_f32_32x32x16_bf16 v[82:97], v[102:105], v[134:137], v[82:97]
	s_waitcnt lgkmcnt(2)
	v_mfma_f32_32x32x16_bf16 v[98:113], v[170:173], v[114:117], v[34:49]
	v_mfma_f32_32x32x16_bf16 v[98:113], v[174:177], v[118:121], v[98:113]
	ds_read_b128 v[170:173], v201 offset:20096
	ds_read_b128 v[174:177], v201 offset:20128
	s_waitcnt lgkmcnt(2)
	v_mfma_f32_32x32x16_bf16 v[98:113], v[242:245], v[122:125], v[98:113]
	v_mfma_f32_32x32x16_bf16 v[98:113], v[246:249], v[126:129], v[98:113]
	ds_read2_b64 v[180:183], v206 offset0:4 offset1:6
	s_waitcnt lgkmcnt(1)
	v_mfma_f32_32x32x16_bf16 v[98:113], v[170:173], v[130:133], v[98:113]
	ds_read2_b64 v[170:173], v206 offset1:2
	v_mfma_f32_32x32x16_bf16 v[98:113], v[174:177], v[134:137], v[98:113]
	v_cvt_pk_bf16_f32 v174, v50, v51
	v_cvt_pk_bf16_f32 v175, v52, v53
	v_cvt_pk_bf16_f32 v176, v54, v55
	v_cvt_pk_bf16_f32 v177, v56, v57
	s_waitcnt lgkmcnt(0)
	s_nop 0
	v_mfma_f32_32x32x16_bf16 v[2:17], v[170:173], v[174:177], v[2:17]
	ds_read2_b64 v[170:173], v207 offset0:32 offset1:34
	s_waitcnt lgkmcnt(0)
	v_mfma_f32_32x32x16_bf16 v[18:33], v[170:173], v[174:177], v[18:33]
	ds_read2_b64 v[174:177], v207 offset0:36 offset1:38
	v_cvt_pk_bf16_f32 v170, v58, v59
	v_cvt_pk_bf16_f32 v171, v60, v61
	v_cvt_pk_bf16_f32 v172, v62, v63
	v_cvt_pk_bf16_f32 v173, v64, v65
	s_nop 1
	v_mfma_f32_32x32x16_bf16 v[2:17], v[180:183], v[170:173], v[2:17]
	ds_read2_b64 v[180:183], v206 offset0:8 offset1:10
	s_waitcnt lgkmcnt(1)
	v_mfma_f32_32x32x16_bf16 v[18:33], v[174:177], v[170:173], v[18:33]
	ds_read2_b64 v[174:177], v207 offset0:40 offset1:42
	v_cvt_pk_bf16_f32 v170, v66, v67
	v_cvt_pk_bf16_f32 v171, v68, v69
	v_cvt_pk_bf16_f32 v172, v70, v71
	v_cvt_pk_bf16_f32 v173, v72, v73
	s_waitcnt lgkmcnt(1)
	s_nop 0
	v_mfma_f32_32x32x16_bf16 v[2:17], v[180:183], v[170:173], v[2:17]
	ds_read2_b64 v[180:183], v206 offset0:12 offset1:14
	s_waitcnt lgkmcnt(1)
	v_mfma_f32_32x32x16_bf16 v[18:33], v[174:177], v[170:173], v[18:33]
	ds_read2_b64 v[174:177], v207 offset0:44 offset1:46
	v_cvt_pk_bf16_f32 v170, v74, v75
	v_cvt_pk_bf16_f32 v171, v76, v77
	v_cvt_pk_bf16_f32 v172, v78, v79
	v_cvt_pk_bf16_f32 v173, v80, v81
	s_waitcnt vmcnt(1)
	ds_write_b128 v190, v[142:145]
	s_waitcnt lgkmcnt(2)
	v_mfma_f32_32x32x16_bf16 v[2:17], v[180:183], v[170:173], v[2:17]
	s_waitcnt lgkmcnt(1)
	v_mfma_f32_32x32x16_bf16 v[18:33], v[174:177], v[170:173], v[18:33]
	s_and_saveexec_b64 s[8:9], s[6:7]
	ds_write_b128 v241, v[138:141]
	s_or_b64 exec, exec, s[8:9]
	s_waitcnt vmcnt(0)
	ds_write2_b64 v208, v[146:147], v[148:149] offset1:1
	s_waitcnt lgkmcnt(0)
	s_barrier
	global_load_dwordx4 v[142:145], v152, s[54:55]
	s_and_saveexec_b64 s[8:9], s[6:7]
	s_cbranch_execz .LBB0_817
	global_load_dwordx4 v[138:141], v150, s[54:55]

.LBB0_889:
	v_exp_f32_e32 v64, v64
	s_waitcnt lgkmcnt(0)
	v_mfma_f32_32x32x16_bf16 v[96:111], v[112:115], v[128:131], v[48:63]
	v_exp_f32_e32 v65, v65
	v_exp_f32_e32 v66, v66
	v_exp_f32_e32 v67, v67
	v_exp_f32_e32 v68, v68
	v_exp_f32_e32 v69, v69
	v_exp_f32_e32 v70, v70
	v_exp_f32_e32 v71, v71
	v_mfma_f32_32x32x16_bf16 v[96:111], v[116:119], v[132:135], v[96:111]
	ds_read_b128 v[112:115], v203 offset:13376
	ds_read_b128 v[116:119], v203 offset:13408
	v_exp_f32_e32 v72, v72
	v_exp_f32_e32 v73, v73
	v_exp_f32_e32 v74, v74
	v_exp_f32_e32 v75, v75
	v_exp_f32_e32 v76, v76
	s_waitcnt lgkmcnt(0)
	v_mfma_f32_32x32x16_bf16 v[96:111], v[112:115], v[136:139], v[96:111]
	v_exp_f32_e32 v77, v77
	v_exp_f32_e32 v78, v78
	v_exp_f32_e32 v79, v79
	v_exp_f32_e32 v80, v80
	v_exp_f32_e32 v81, v81
	v_exp_f32_e32 v82, v82
	v_exp_f32_e32 v83, v83
	v_mfma_f32_32x32x16_bf16 v[96:111], v[116:119], v[140:143], v[96:111]
	ds_read_b128 v[112:115], v203 offset:13440
	ds_read_b128 v[116:119], v203 offset:13472
	ds_read_b128 v[156:159], v203 offset:19968
	ds_read_b128 v[160:163], v203 offset:20000
	ds_read_b128 v[248:251], v203 offset:20032
	ds_read_b128 v[252:255], v203 offset:20064
	v_exp_f32_e32 v84, v84
	v_exp_f32_e32 v85, v85
	v_exp_f32_e32 v86, v86
	v_exp_f32_e32 v87, v87
	v_exp_f32_e32 v88, v88
	s_waitcnt lgkmcnt(4)
	v_mfma_f32_32x32x16_bf16 v[96:111], v[112:115], v[144:147], v[96:111]
	v_exp_f32_e32 v89, v89
	v_exp_f32_e32 v90, v90
	v_exp_f32_e32 v91, v91
	v_exp_f32_e32 v92, v92
	v_exp_f32_e32 v93, v93
	v_exp_f32_e32 v94, v94
	v_exp_f32_e32 v95, v95
	v_mfma_f32_32x32x16_bf16 v[96:111], v[116:119], v[148:151], v[96:111]
	s_waitcnt lgkmcnt(2)
	v_mfma_f32_32x32x16_bf16 v[112:127], v[156:159], v[128:131], v[48:63]
	v_mfma_f32_32x32x16_bf16 v[112:127], v[160:163], v[132:135], v[112:127]
	ds_read_b128 v[156:159], v203 offset:20096
	ds_read_b128 v[160:163], v203 offset:20128
	s_waitcnt lgkmcnt(2)
	v_mfma_f32_32x32x16_bf16 v[112:127], v[248:251], v[136:139], v[112:127]
	v_mfma_f32_32x32x16_bf16 v[112:127], v[252:255], v[140:143], v[112:127]
	ds_read2_b64 v[188:191], v244 offset0:4 offset1:6
	s_waitcnt lgkmcnt(1)
	v_mfma_f32_32x32x16_bf16 v[112:127], v[156:159], v[144:147], v[112:127]
	ds_read2_b64 v[156:159], v244 offset1:2
	v_mfma_f32_32x32x16_bf16 v[112:127], v[160:163], v[148:151], v[112:127]
	v_cvt_pk_bf16_f32 v160, v64, v65
	v_cvt_pk_bf16_f32 v161, v66, v67
	v_cvt_pk_bf16_f32 v162, v68, v69
	v_cvt_pk_bf16_f32 v163, v70, v71
	s_waitcnt lgkmcnt(0)
	s_nop 0
	v_mfma_f32_32x32x16_bf16 v[32:47], v[156:159], v[160:163], v[32:47]
	ds_read2_b64 v[156:159], v245 offset0:32 offset1:34
	s_waitcnt lgkmcnt(0)
	v_mfma_f32_32x32x16_bf16 v[16:31], v[156:159], v[160:163], v[16:31]
	ds_read2_b64 v[160:163], v245 offset0:36 offset1:38
	v_cvt_pk_bf16_f32 v156, v72, v73
	v_cvt_pk_bf16_f32 v157, v74, v75
	v_cvt_pk_bf16_f32 v158, v76, v77
	v_cvt_pk_bf16_f32 v159, v78, v79
	s_nop 1
	v_mfma_f32_32x32x16_bf16 v[32:47], v[188:191], v[156:159], v[32:47]
	ds_read2_b64 v[188:191], v244 offset0:8 offset1:10
	s_waitcnt lgkmcnt(1)
	v_mfma_f32_32x32x16_bf16 v[16:31], v[160:163], v[156:159], v[16:31]
	ds_read2_b64 v[160:163], v245 offset0:40 offset1:42
	v_cvt_pk_bf16_f32 v156, v80, v81
	v_cvt_pk_bf16_f32 v157, v82, v83
	v_cvt_pk_bf16_f32 v158, v84, v85
	v_cvt_pk_bf16_f32 v159, v86, v87
	s_waitcnt lgkmcnt(1)
	s_nop 0
	v_mfma_f32_32x32x16_bf16 v[32:47], v[188:191], v[156:159], v[32:47]
	ds_read2_b64 v[188:191], v244 offset0:12 offset1:14
	s_waitcnt lgkmcnt(1)
	v_mfma_f32_32x32x16_bf16 v[16:31], v[160:163], v[156:159], v[16:31]
	ds_read2_b64 v[160:163], v245 offset0:44 offset1:46
	v_cvt_pk_bf16_f32 v156, v88, v89
	v_cvt_pk_bf16_f32 v157, v90, v91
	v_cvt_pk_bf16_f32 v158, v92, v93
	v_cvt_pk_bf16_f32 v159, v94, v95
	s_waitcnt vmcnt(1)
	ds_write_b128 v201, v[2:5]
	s_waitcnt lgkmcnt(2)
	v_mfma_f32_32x32x16_bf16 v[32:47], v[188:191], v[156:159], v[32:47]
	s_waitcnt lgkmcnt(1)
	v_mfma_f32_32x32x16_bf16 v[16:31], v[160:163], v[156:159], v[16:31]
	s_and_saveexec_b64 s[8:9], s[6:7]
	ds_write_b128 v169, v[152:155]
	s_or_b64 exec, exec, s[8:9]
	s_waitcnt vmcnt(0)
	ds_write2_b64 v243, v[6:7], v[8:9] offset1:1
	s_waitcnt lgkmcnt(0)
	s_barrier
	global_load_dwordx4 v[156:159], v180, s[54:55]
	s_and_saveexec_b64 s[8:9], s[6:7]
	s_cbranch_execz .LBB0_873
	global_load_dwordx4 v[152:155], v178, s[54:55]
	s_branch .LBB0_873
